# v12 plus GEMM1 epilogue preludes: fourth bias-row LDS read issued with the other three (one LDS round trip per 16-token block instead of two)
# baseline (speedup 1.0000x reference)
.LBB0_565:
	v_mov_b32_e32 v86, v161
	v_mov_b32_e32 v87, v162
	v_mov_b32_e32 v161, v163
	v_pk_add_f32 v[86:87], v[86:87], v[160:161]
	v_mov_b32_e32 v160, v157
	v_mov_b32_e32 v161, v158
	v_mov_b32_e32 v157, v159
	v_pk_add_f32 v[156:157], v[160:161], v[156:157]
	v_add_f32_e32 v86, v86, v87
	v_pk_add_f32 v[156:157], v[156:157], v[156:157] op_sel:[0,1] op_sel_hi:[1,0]
	v_add_f32_e32 v86, 0, v86
	v_add_f32_e32 v152, v152, v153
	v_add_f32_e32 v154, v154, v155
	v_mov_b32_e32 v87, v82
	v_mov_b32_e32 v157, v83
	v_mov_b32_e32 v153, v84
	v_mov_b32_e32 v155, v85
	v_pk_add_f32 v[82:83], v[86:87], v[156:157]
	v_pk_add_f32 v[84:85], v[152:153], v[154:155]
	v_add_f32_e32 v4, v4, v5
	v_pk_add_f32 v[82:83], v[82:83], v[84:85]
	v_mov_b32_e32 v84, v13
	v_mov_b32_e32 v85, v14
	v_mov_b32_e32 v13, v15
	v_mov_b32_e32 v14, v9
	v_mov_b32_e32 v15, v10
	v_mov_b32_e32 v9, v11
	v_pk_add_f32 v[12:13], v[84:85], v[12:13]
	v_pk_add_f32 v[8:9], v[14:15], v[8:9]
	v_add_f32_e32 v12, v12, v13
	v_pk_add_f32 v[8:9], v[8:9], v[8:9] op_sel:[0,1] op_sel_hi:[1,0]
	v_add_f32_e32 v12, 0, v12
	v_add_f32_e32 v6, v6, v7
	v_mov_b32_e32 v13, v0
	v_mov_b32_e32 v9, v1
	v_mov_b32_e32 v5, v2
	v_mov_b32_e32 v7, v3
	v_pk_add_f32 v[0:1], v[12:13], v[8:9]
	v_pk_add_f32 v[2:3], v[4:5], v[6:7]
	s_mov_b32 s0, 0x3a800000
	v_pk_add_f32 v[0:1], v[0:1], v[2:3]
	v_mov_b32_e32 v3, v82
	v_mov_b32_e32 v2, v0
	v_mov_b32_e32 v82, v1
	v_pk_add_f32 v[0:1], v[2:3], v[82:83]
	s_add_i32 s48, s56, s64
	v_pk_fma_f32 v[0:1], v[0:1], s[0:1], v[180:181] op_sel_hi:[1,0,0]
	s_ashr_i32 s49, s48, 31
	v_mul_f32_e32 v2, 0x4b800000, v1
	v_cmp_gt_f32_e32 vcc, s66, v1
	v_cmp_gt_f32_e64 s[40:41], s66, v0
	s_lshl_b64 s[18:19], s[48:49], 8
	v_cndmask_b32_e32 v1, v1, v2, vcc
	v_mul_f32_e32 v2, 0x4b800000, v0
	v_rsq_f32_e32 v1, v1
	v_cndmask_b32_e64 v0, v0, v2, s[40:41]
	v_rsq_f32_e32 v0, v0
	s_cmp_lt_u32 s51, 16
	v_mul_f32_e32 v2, 0x45800000, v1
	v_cndmask_b32_e32 v193, v1, v2, vcc
	v_mul_f32_e32 v1, 0x45800000, v0
	v_writelane_b32 v254, s18, 39
	v_mov_b32_e32 v194, v188
	s_cselect_b64 s[28:29], -1, 0
	s_add_i32 s0, s51, -16
	v_cndmask_b32_e64 v192, v0, v1, s[40:41]
	v_writelane_b32 v254, s19, 40
	s_mov_b64 s[18:19], s[88:89]
	s_lshr_b32 s0, s0, 2
	v_lshl_add_u32 v0, v194, 2, s7
	v_writelane_b32 v254, s28, 37
	s_cmp_gt_u32 s51, 15
	ds_write2st64_b32 v0, v80, v223 offset1:1
	v_writelane_b32 v254, s29, 38
	s_cselect_b64 s[28:29], -1, 0
	s_nop 1
	v_readlane_b32 s40, v252, 1
	s_and_b64 s[34:35], s[28:29], exec
	v_readlane_b32 s41, v252, 2
	v_readlane_b32 s42, v252, 3
	v_readlane_b32 s43, v252, 4
	v_and_b32_e32 v195, 15, v194
	v_ashrrev_i32_e32 v172, 4, v194
	s_cselect_b32 s17, s0, s51
	s_mov_b64 s[42:43], s[40:41]
	s_andn2_b64 vcc, exec, s[26:27]
	s_cbranch_vccnz .LBB0_577
	v_lshlrev_b32_e32 v1, 2, v172
	v_or_b32_e32 v3, 1, v1
	v_cvt_f32_i32_e32 v2, v1
	v_cvt_f32_i32_e32 v3, v3
	v_and_b32_e32 v0, -16, v194
	v_add_u32_e32 v201, s7, v0
	v_add_u32_e32 v196, s97, v0
	v_mul_f32_e32 v0, 0xbf549a78, v2
	v_mul_f32_e32 v2, 0xbf549a78, v3
	v_or_b32_e32 v3, 2, v1
	v_cvt_f32_i32_e32 v3, v3
	v_exp_f32_e32 v0, v0
	v_exp_f32_e32 v2, v2
	s_mov_b32 s67, s56
	v_mul_f32_e32 v3, 0xbf549a78, v3
	v_exp_f32_e32 v3, v3
	s_add_i32 s56, s2, s56
	s_and_b64 s[26:27], s[28:29], exec
	s_movk_i32 s0, 0x3e0
	s_cselect_b32 s59, s0, 0xe0
	s_cmp_gt_i32 s58, 1
	v_mul_f32_e32 v200, 0.15915494, v0
	v_and_b32_e32 v0, 4, v1
	s_cselect_b64 s[46:47], -1, 0
	s_cmp_gt_u32 s3, 3
	v_or_b32_e32 v4, 3, v1
	v_mul_f32_e32 v199, 0.15915494, v2
	v_mul_f32_e32 v198, 0.15915494, v3
	v_cvt_f32_ubyte0_e32 v1, v0
	v_or_b32_e32 v2, 1, v0
	v_or_b32_e32 v3, 2, v0
	v_or_b32_e32 v0, 3, v0
	s_cselect_b64 s[90:91], -1, 0
	s_cmp_gt_u32 s3, 5
	v_cvt_f32_ubyte0_e32 v0, v0
	s_cselect_b64 s[26:27], -1, 0
	s_cmp_gt_u32 s58, 8
	v_mul_f32_e32 v0, 0xbfd49a78, v0
	s_cselect_b64 s[2:3], -1, 0
	v_cvt_f32_ubyte0_e32 v2, v2
	v_cvt_f32_ubyte0_e32 v3, v3
	v_exp_f32_e32 v0, v0
	v_writelane_b32 v254, s2, 34
	s_cmp_gt_u32 s58, 12
	v_mul_f32_e32 v1, 0xbfd49a78, v1
	v_mul_f32_e32 v2, 0xbfd49a78, v2
	v_mul_f32_e32 v3, 0xbfd49a78, v3
	v_writelane_b32 v254, s3, 35
	v_cvt_f32_i32_e32 v4, v4
	s_cselect_b64 s[2:3], -1, 0
	v_exp_f32_e32 v1, v1
	v_exp_f32_e32 v2, v2
	v_exp_f32_e32 v3, v3
	v_writelane_b32 v254, s2, 44
	v_mul_f32_e32 v175, 0.15915494, v0
	v_or_b32_e32 v0, v195, v206
	v_writelane_b32 v254, s3, 45
	v_cmp_lt_i32_e64 s[2:3], 1, v172
	v_lshlrev_b32_e32 v231, 2, v0
	v_mul_f32_e32 v4, 0xbf549a78, v4
	v_writelane_b32 v254, s2, 50
	v_mul_f32_e32 v224, 0.15915494, v1
	v_mul_f32_e32 v223, 0.15915494, v2
	v_writelane_b32 v254, s3, 51
	v_mul_f32_e32 v203, 0.15915494, v3
	v_cmp_gt_u32_e64 s[2:3], 16, v194
	ds_bpermute_b32 v80, v231, v193
	ds_read_b128 v[0:3], v201
	v_exp_f32_e32 v4, v4
	v_writelane_b32 v254, s2, 46
	s_add_i32 s0, s8, 0xfffffa80
	ds_read_b128 v[12:15], v201 offset:128
	v_writelane_b32 v254, s3, 47
	s_ashr_i32 s2, s0, 6
	s_ashr_i32 s3, s2, 31
	s_lshl_b64 s[2:3], s[2:3], 2
	v_mul_f32_e32 v197, 0.15915494, v4
	s_add_u32 s0, s18, s2
	ds_read_b128 v[4:7], v201 offset:64
	ds_read_b128 v[152:155], v201 offset:192
	s_waitcnt lgkmcnt(0)
	v_pk_fma_f32 v[10:11], v[150:151], v[80:81], v[2:3] op_sel_hi:[1,0,1]
	v_pk_fma_f32 v[8:9], v[148:149], v[80:81], v[0:1] op_sel_hi:[1,0,1]
	s_addc_u32 s2, s19, s3
	s_add_u32 s8, s0, 0x280000
	s_addc_u32 s9, s2, 0
	s_and_b32 s2, s56, s59
	v_writelane_b32 v254, s8, 48
	s_lshr_b32 s0, s2, 6
	v_pk_fma_f32 v[156:157], v[144:145], v[80:81], v[4:5] op_sel_hi:[1,0,1]
	v_writelane_b32 v254, s9, 49
	v_pk_fma_f32 v[158:159], v[146:147], v[80:81], v[6:7] op_sel_hi:[1,0,1]
	v_pk_fma_f32 v[12:13], v[140:141], v[80:81], v[12:13] op_sel_hi:[1,0,1]
	v_pk_fma_f32 v[14:15], v[142:143], v[80:81], v[14:15] op_sel_hi:[1,0,1]
	s_waitcnt lgkmcnt(0)
	v_pk_fma_f32 v[152:153], v[136:137], v[80:81], v[152:153] op_sel_hi:[1,0,1]
	v_pk_fma_f32 v[154:155], v[138:139], v[80:81], v[154:155] op_sel_hi:[1,0,1]
	v_cvt_f32_ubyte0_e32 v228, s0
	v_cvt_f32_ubyte0_e32 v229, v195
	s_mov_b64 s[8:9], -1
	s_and_b64 vcc, exec, s[46:47]
	s_cbranch_vccz .LBB0_616
	s_and_b64 vcc, exec, s[90:91]
	s_cbranch_vccz .LBB0_610
	s_and_b64 vcc, exec, s[26:27]
	s_cbranch_vccz .LBB0_607
	v_readlane_b32 s34, v254, 34
	v_readlane_b32 s35, v254, 35
	s_and_b64 vcc, exec, s[34:35]
	s_cbranch_vccz .LBB0_603
	s_cmp_lt_i32 s58, 10
	s_cbranch_scc1 .LBB0_597
	s_cmp_lg_u32 s58, 10
	s_cbranch_scc0 .LBB0_594
	v_readlane_b32 s34, v254, 44
	v_readlane_b32 s35, v254, 45
	s_and_b64 vcc, exec, s[34:35]
	s_cbranch_vccz .LBB0_590
	s_cmp_gt_i32 s58, 21
	s_cbranch_scc0 .LBB0_581
	v_readlane_b32 s8, v255, 0
	v_readlane_b32 s9, v255, 1
	s_andn2_b64 vcc, exec, s[8:9]
	s_cbranch_vccnz .LBB0_580
	s_andn2_b64 vcc, exec, s[28:29]
	s_cbranch_vccnz .LBB0_578
	v_mul_f32_e32 v0, v224, v228
	v_sin_f32_e32 v5, v0
	v_mul_f32_e32 v1, v224, v229
	v_sin_f32_e32 v80, v1
	v_cos_f32_e32 v4, v1
	v_mul_f32_e32 v1, v223, v228
	v_readlane_b32 s8, v254, 50
	ds_bpermute_b32 v2, v219, v8
	v_sin_f32_e32 v7, v1
	ds_bpermute_b32 v3, v219, v9
	v_readlane_b32 s9, v254, 51
	ds_bpermute_b32 v6, v219, v156
	ds_bpermute_b32 v161, v219, v11
	v_cndmask_b32_e64 v82, -v5, v5, s[8:9]
	v_mul_f32_e32 v5, v223, v229
	v_sin_f32_e32 v84, v5
	v_cndmask_b32_e64 v83, -v7, v7, s[8:9]
	s_waitcnt lgkmcnt(0)
	v_pk_mul_f32 v[2:3], v[82:83], v[2:3]
	ds_bpermute_b32 v7, v219, v157
	v_cndmask_b32_e64 v82, -v80, v80, s[8:9]
	v_mul_f32_e32 v80, v203, v228
	v_cndmask_b32_e64 v83, -v84, v84, s[8:9]
	v_cos_f32_e32 v84, v80
	s_waitcnt lgkmcnt(0)
	v_pk_mul_f32 v[6:7], v[82:83], v[6:7]
	v_sin_f32_e32 v80, v80
	ds_bpermute_b32 v83, v219, v10
	v_mul_f32_e32 v82, v84, v10
	v_mul_f32_e32 v84, v203, v229
	v_cos_f32_e32 v85, v84
	v_sin_f32_e32 v87, v84
	v_cndmask_b32_e64 v80, -v80, v80, s[8:9]
	s_waitcnt lgkmcnt(0)
	v_mul_f32_e32 v84, v80, v83
	v_mul_f32_e32 v86, v85, v158
	v_mul_f32_e32 v85, v175, v228
	v_cndmask_b32_e64 v83, -v87, v87, s[8:9]
	v_sin_f32_e32 v87, v85
	v_cos_f32_e32 v0, v0
	v_cos_f32_e32 v1, v1
	ds_bpermute_b32 v80, v219, v158
	v_cos_f32_e32 v162, v85
	v_cndmask_b32_e64 v163, -v87, v87, s[8:9]
	v_mov_b32_e32 v160, v11
	v_pk_fma_f32 v[0:1], v[0:1], v[8:9], v[2:3]
	v_pk_mul_f32 v[160:161], v[162:163], v[160:161]
	v_mul_f32_e32 v2, v175, v229
	s_waitcnt lgkmcnt(0)
	v_mul_f32_e32 v164, v83, v80
	v_mov_b32_e32 v85, v161
	v_sin_f32_e32 v80, v2
	ds_bpermute_b32 v161, v219, v159
	v_cos_f32_e32 v162, v2
	v_cos_f32_e32 v5, v5
	v_mov_b32_e32 v83, v160
	v_cndmask_b32_e64 v163, -v80, v80, s[8:9]
	v_mov_b32_e32 v160, v159
	v_pk_add_f32 v[2:3], v[82:83], v[84:85]
	s_waitcnt lgkmcnt(0)
	v_pk_mul_f32 v[82:83], v[162:163], v[160:161]
	v_pk_fma_f32 v[4:5], v[4:5], v[156:157], v[6:7]
	v_mov_b32_e32 v87, v82
	v_mov_b32_e32 v165, v83
	v_pk_add_f32 v[6:7], v[86:87], v[164:165]
	s_branch .LBB0_579

.LBB0_620:
	v_lshlrev_b32_e32 v8, 3, v194
	v_readlane_b32 s8, v254, 10
	v_and_b32_e32 v8, 24, v8
	s_lshl_b32 s0, s17, 2
	v_readlane_b32 s9, v254, 11
	v_lshlrev_b32_e32 v80, 1, v8
	s_add_i32 s34, s0, s8
	v_lshl_add_u32 v174, v8, 2, s97
	v_lshl_add_u64 v[8:9], s[18:19], 0, v[80:81]
	s_mov_b64 s[8:9], 0x5800000
	v_or_b32_e32 v202, 16, v195
	v_lshl_add_u64 v[176:177], v[8:9], 0, s[8:9]
	v_or_b32_e32 v8, v202, v206
	v_lshlrev_b32_e32 v232, 2, v8
	ds_bpermute_b32 v80, v232, v193
	ds_read_b128 v[8:11], v201
	ds_read_b128 v[12:15], v201 offset:64
	ds_read_b128 v[152:155], v201 offset:128
	s_lshl_b64 s[36:37], s[48:49], 11
	s_lshl_b64 s[8:9], s[48:49], 9
	ds_read_b128 v[156:159], v201 offset:192
	s_waitcnt lgkmcnt(0)
	v_pk_fma_f32 v[84:85], v[134:135], v[80:81], v[10:11] op_sel_hi:[1,0,1]
	v_pk_fma_f32 v[82:83], v[132:133], v[80:81], v[8:9] op_sel_hi:[1,0,1]
	s_mul_hi_i32 s29, s48, 0x300
	s_mul_i32 s28, s48, 0x300
	v_writelane_b32 v254, s36, 54
	s_ashr_i32 s35, s34, 31
	s_waitcnt lgkmcnt(0)
	v_pk_fma_f32 v[156:157], v[120:121], v[80:81], v[156:157] op_sel_hi:[1,0,1]
	v_cndmask_b32_e64 v8, 0, 1, s[46:47]
	v_cmp_ne_u32_e64 s[48:49], 1, v8
	v_cndmask_b32_e64 v8, 0, 1, s[90:91]
	v_ashrrev_i32_e32 v86, 3, v194
	v_ashrrev_i32_e32 v226, 2, v194
	v_writelane_b32 v254, s37, 55
	v_or_b32_e32 v225, 16, v194
	v_pk_fma_f32 v[160:161], v[128:129], v[80:81], v[12:13] op_sel_hi:[1,0,1]
	v_pk_fma_f32 v[162:163], v[130:131], v[80:81], v[14:15] op_sel_hi:[1,0,1]
	v_pk_fma_f32 v[152:153], v[124:125], v[80:81], v[152:153] op_sel_hi:[1,0,1]
	v_pk_fma_f32 v[154:155], v[126:127], v[80:81], v[154:155] op_sel_hi:[1,0,1]
	v_pk_fma_f32 v[158:159], v[122:123], v[80:81], v[158:159] op_sel_hi:[1,0,1]
	v_cvt_f32_ubyte0_e32 v227, v202
	s_mov_b64 s[44:45], -1
	s_andn2_b64 vcc, exec, s[46:47]
	v_cmp_ne_u32_e64 s[46:47], 1, v8
	s_cbranch_vccnz .LBB0_698
	s_and_b64 vcc, exec, s[46:47]
	s_cbranch_vccnz .LBB0_691
	s_andn2_b64 vcc, exec, s[26:27]
	s_cbranch_vccnz .LBB0_687
	v_readlane_b32 s36, v254, 34
	v_readlane_b32 s37, v254, 35
	s_andn2_b64 vcc, exec, s[36:37]
	s_cbranch_vccnz .LBB0_680
	s_cmp_lt_i32 s58, 10
	s_cbranch_scc1 .LBB0_667
	s_cmp_lg_u32 s58, 10
	s_cbranch_scc0 .LBB0_657
	v_readlane_b32 s36, v254, 44
	v_readlane_b32 s37, v254, 45
	s_andn2_b64 vcc, exec, s[36:37]
	s_cbranch_vccnz .LBB0_651
	s_cmp_gt_i32 s58, 21
	s_cbranch_scc0 .LBB0_641
	v_readlane_b32 s36, v255, 0
	v_readlane_b32 s37, v255, 1
	s_andn2_b64 vcc, exec, s[36:37]
	s_cbranch_vccnz .LBB0_640
	s_and_b64 vcc, exec, s[40:41]
	s_cbranch_vccnz .LBB0_634
	v_mul_f32_e32 v8, v224, v228
	v_sin_f32_e32 v13, v8
	v_mul_f32_e32 v9, v224, v227
	v_sin_f32_e32 v80, v9
	v_cos_f32_e32 v12, v9
	v_mul_f32_e32 v9, v223, v228
	v_readlane_b32 s36, v254, 50
	ds_bpermute_b32 v10, v219, v82
	v_sin_f32_e32 v15, v9
	ds_bpermute_b32 v11, v219, v83
	v_readlane_b32 s37, v254, 51
	ds_bpermute_b32 v14, v219, v160
	ds_bpermute_b32 v171, v219, v85
	v_cndmask_b32_e64 v164, -v13, v13, s[36:37]
	v_mul_f32_e32 v13, v223, v227
	v_sin_f32_e32 v87, v13
	v_cndmask_b32_e64 v165, -v15, v15, s[36:37]
	ds_bpermute_b32 v15, v219, v161
	s_waitcnt lgkmcnt(0)
	v_pk_mul_f32 v[10:11], v[164:165], v[10:11]
	v_cndmask_b32_e64 v164, -v80, v80, s[36:37]
	v_mul_f32_e32 v80, v203, v228
	v_cndmask_b32_e64 v165, -v87, v87, s[36:37]
	v_cos_f32_e32 v87, v80
	v_sin_f32_e32 v80, v80
	v_pk_mul_f32 v[14:15], v[164:165], v[14:15]
	ds_bpermute_b32 v165, v219, v84
	v_mul_f32_e32 v164, v87, v84
	v_mul_f32_e32 v87, v203, v227
	v_cos_f32_e32 v167, v87
	v_cndmask_b32_e64 v80, -v80, v80, s[36:37]
	s_waitcnt lgkmcnt(0)
	v_mul_f32_e32 v166, v80, v165
	v_mul_f32_e32 v165, v175, v228
	v_mul_f32_e32 v168, v167, v162
	v_sin_f32_e32 v167, v165
	v_cos_f32_e32 v8, v8
	v_cos_f32_e32 v9, v9
	v_sin_f32_e32 v87, v87
	ds_bpermute_b32 v80, v219, v162
	v_cos_f32_e32 v178, v165
	v_cndmask_b32_e64 v179, -v167, v167, s[36:37]
	v_mov_b32_e32 v170, v85
	v_cndmask_b32_e64 v87, -v87, v87, s[36:37]
	v_pk_mul_f32 v[170:171], v[178:179], v[170:171]
	v_pk_fma_f32 v[8:9], v[8:9], v[82:83], v[10:11]
	v_mul_f32_e32 v10, v175, v227
	s_waitcnt lgkmcnt(0)
	v_mul_f32_e32 v182, v87, v80
	v_mov_b32_e32 v167, v171
	v_sin_f32_e32 v80, v10
	ds_bpermute_b32 v171, v219, v163
	v_cos_f32_e32 v178, v10
	v_cos_f32_e32 v13, v13
	v_mov_b32_e32 v165, v170
	v_cndmask_b32_e64 v179, -v80, v80, s[36:37]
	v_mov_b32_e32 v170, v163
	v_pk_add_f32 v[10:11], v[164:165], v[166:167]
	s_waitcnt lgkmcnt(0)
	v_pk_mul_f32 v[164:165], v[178:179], v[170:171]
	v_pk_fma_f32 v[12:13], v[12:13], v[160:161], v[14:15]
	v_mov_b32_e32 v169, v164
	v_mov_b32_e32 v183, v165
	v_pk_add_f32 v[14:15], v[168:169], v[182:183]
	s_branch .LBB0_635

.LBB0_704:
	v_or_b32_e32 v87, 32, v195
	v_or_b32_e32 v0, v87, v206
	v_lshlrev_b32_e32 v233, 2, v0
	ds_read_b128 v[0:3], v201
	ds_bpermute_b32 v80, v233, v193
	ds_read_b128 v[4:7], v201 offset:64
	ds_read_b128 v[152:155], v201 offset:128
	s_or_b32 s90, s56, 32
	s_and_b32 s2, s90, s59
	s_lshr_b32 s0, s2, 6
	ds_read_b128 v[156:159], v201 offset:192
	s_waitcnt lgkmcnt(0)
	v_pk_fma_f32 v[84:85], v[118:119], v[80:81], v[2:3] op_sel_hi:[1,0,1]
	v_pk_fma_f32 v[82:83], v[116:117], v[80:81], v[0:1] op_sel_hi:[1,0,1]
	v_pk_fma_f32 v[160:161], v[112:113], v[80:81], v[4:5] op_sel_hi:[1,0,1]
	v_pk_fma_f32 v[162:163], v[114:115], v[80:81], v[6:7] op_sel_hi:[1,0,1]
	v_pk_fma_f32 v[152:153], v[108:109], v[80:81], v[152:153] op_sel_hi:[1,0,1]
	v_pk_fma_f32 v[154:155], v[110:111], v[80:81], v[154:155] op_sel_hi:[1,0,1]
	s_waitcnt lgkmcnt(0)
	v_pk_fma_f32 v[156:157], v[104:105], v[80:81], v[156:157] op_sel_hi:[1,0,1]
	v_pk_fma_f32 v[158:159], v[106:107], v[80:81], v[158:159] op_sel_hi:[1,0,1]
	v_cvt_f32_ubyte0_e32 v235, s0
	v_cvt_f32_ubyte0_e32 v230, v87
	s_and_b64 vcc, exec, s[48:49]
	s_mov_b64 s[44:45], -1
	s_cbranch_vccnz .LBB0_755
	s_and_b64 vcc, exec, s[46:47]
	s_cbranch_vccnz .LBB0_749
	s_andn2_b64 vcc, exec, s[26:27]
	s_cbranch_vccnz .LBB0_746
	v_readlane_b32 s36, v254, 34
	v_readlane_b32 s37, v254, 35
	s_andn2_b64 vcc, exec, s[36:37]
	s_cbranch_vccnz .LBB0_740
	s_cmp_lt_i32 s58, 10
	s_cbranch_scc1 .LBB0_734
	s_cmp_lg_u32 s58, 10
	s_cbranch_scc0 .LBB0_731
	v_readlane_b32 s36, v254, 44
	v_readlane_b32 s37, v254, 45
	s_andn2_b64 vcc, exec, s[36:37]
	s_cbranch_vccnz .LBB0_726
	s_cmp_gt_i32 s58, 21
	s_cbranch_scc0 .LBB0_718
	v_readlane_b32 s36, v255, 0
	v_readlane_b32 s37, v255, 1
	s_andn2_b64 vcc, exec, s[36:37]
	s_cbranch_vccnz .LBB0_717
	s_and_b64 vcc, exec, s[40:41]
	s_cbranch_vccnz .LBB0_715
	v_mul_f32_e32 v0, v224, v235
	v_sin_f32_e32 v5, v0
	v_mul_f32_e32 v1, v224, v230
	v_sin_f32_e32 v80, v1
	v_cos_f32_e32 v4, v1
	v_mul_f32_e32 v1, v223, v235
	v_readlane_b32 s36, v254, 50
	ds_bpermute_b32 v2, v219, v82
	v_sin_f32_e32 v7, v1
	ds_bpermute_b32 v3, v219, v83
	v_readlane_b32 s37, v254, 51
	ds_bpermute_b32 v6, v219, v160
	ds_bpermute_b32 v171, v219, v85
	v_cndmask_b32_e64 v164, -v5, v5, s[36:37]
	v_mul_f32_e32 v5, v223, v230
	v_sin_f32_e32 v87, v5
	v_cndmask_b32_e64 v165, -v7, v7, s[36:37]
	ds_bpermute_b32 v7, v219, v161
	s_waitcnt lgkmcnt(0)
	v_pk_mul_f32 v[2:3], v[164:165], v[2:3]
	v_cndmask_b32_e64 v164, -v80, v80, s[36:37]
	v_mul_f32_e32 v80, v203, v235
	v_cndmask_b32_e64 v165, -v87, v87, s[36:37]
	v_cos_f32_e32 v87, v80
	v_sin_f32_e32 v80, v80
	v_pk_mul_f32 v[6:7], v[164:165], v[6:7]
	ds_bpermute_b32 v165, v219, v84
	v_mul_f32_e32 v164, v87, v84
	v_mul_f32_e32 v87, v203, v230
	v_cos_f32_e32 v167, v87
	v_cndmask_b32_e64 v80, -v80, v80, s[36:37]
	s_waitcnt lgkmcnt(0)
	v_mul_f32_e32 v166, v80, v165
	v_mul_f32_e32 v165, v175, v235
	v_mul_f32_e32 v168, v167, v162
	v_sin_f32_e32 v167, v165
	v_cos_f32_e32 v0, v0
	v_cos_f32_e32 v1, v1
	v_sin_f32_e32 v87, v87
	ds_bpermute_b32 v80, v219, v162
	v_cos_f32_e32 v178, v165
	v_cndmask_b32_e64 v179, -v167, v167, s[36:37]
	v_mov_b32_e32 v170, v85
	v_cndmask_b32_e64 v87, -v87, v87, s[36:37]
	v_pk_mul_f32 v[170:171], v[178:179], v[170:171]
	v_pk_fma_f32 v[0:1], v[0:1], v[82:83], v[2:3]
	v_mul_f32_e32 v2, v175, v230
	s_waitcnt lgkmcnt(0)
	v_mul_f32_e32 v182, v87, v80
	v_mov_b32_e32 v167, v171
	v_sin_f32_e32 v80, v2
	ds_bpermute_b32 v171, v219, v163
	v_cos_f32_e32 v178, v2
	v_cos_f32_e32 v5, v5
	v_mov_b32_e32 v165, v170
	v_cndmask_b32_e64 v179, -v80, v80, s[36:37]
	v_mov_b32_e32 v170, v163
	v_pk_add_f32 v[2:3], v[164:165], v[166:167]
	s_waitcnt lgkmcnt(0)
	v_pk_mul_f32 v[164:165], v[178:179], v[170:171]
	v_pk_fma_f32 v[4:5], v[4:5], v[160:161], v[6:7]
	v_mov_b32_e32 v169, v164
	v_mov_b32_e32 v183, v165
	v_pk_add_f32 v[6:7], v[168:169], v[182:183]
	s_branch .LBB0_716

.LBB0_759:
	v_or_b32_e32 v87, 48, v195
	v_or_b32_e32 v8, v87, v206
	v_lshlrev_b32_e32 v234, 2, v8
	ds_bpermute_b32 v80, v234, v193
	ds_read_b128 v[8:11], v201
	ds_read_b128 v[12:15], v201 offset:64
	ds_read_b128 v[152:155], v201 offset:128
	v_cvt_f32_ubyte0_e32 v228, v87
	s_and_b64 vcc, exec, s[48:49]
	s_mov_b64 s[44:45], -1
	ds_read_b128 v[156:159], v201 offset:192
	s_waitcnt lgkmcnt(0)
	v_pk_fma_f32 v[84:85], v[102:103], v[80:81], v[10:11] op_sel_hi:[1,0,1]
	v_pk_fma_f32 v[82:83], v[100:101], v[80:81], v[8:9] op_sel_hi:[1,0,1]
	v_pk_fma_f32 v[160:161], v[96:97], v[80:81], v[12:13] op_sel_hi:[1,0,1]
	v_pk_fma_f32 v[162:163], v[98:99], v[80:81], v[14:15] op_sel_hi:[1,0,1]
	v_pk_fma_f32 v[152:153], v[92:93], v[80:81], v[152:153] op_sel_hi:[1,0,1]
	v_pk_fma_f32 v[154:155], v[94:95], v[80:81], v[154:155] op_sel_hi:[1,0,1]
	s_waitcnt lgkmcnt(0)
	v_pk_fma_f32 v[156:157], v[88:89], v[80:81], v[156:157] op_sel_hi:[1,0,1]
	v_pk_fma_f32 v[158:159], v[90:91], v[80:81], v[158:159] op_sel_hi:[1,0,1]
	s_cbranch_vccnz .LBB0_834
	s_and_b64 vcc, exec, s[46:47]
	s_cbranch_vccnz .LBB0_827
	s_andn2_b64 vcc, exec, s[26:27]
	s_cbranch_vccnz .LBB0_823
	v_readlane_b32 s36, v254, 34
	v_readlane_b32 s37, v254, 35
	s_andn2_b64 vcc, exec, s[36:37]
	s_cbranch_vccnz .LBB0_816
	s_cmp_lt_i32 s58, 10
	s_cbranch_scc1 .LBB0_803
	s_cmp_lg_u32 s58, 10
	s_cbranch_scc0 .LBB0_793
	v_readlane_b32 s36, v254, 44
	v_readlane_b32 s37, v254, 45
	s_andn2_b64 vcc, exec, s[36:37]
	s_cbranch_vccnz .LBB0_787
	s_cmp_gt_i32 s58, 21
	s_cbranch_scc0 .LBB0_777
	v_readlane_b32 s36, v255, 0
	v_readlane_b32 s37, v255, 1
	s_andn2_b64 vcc, exec, s[36:37]
	s_cbranch_vccnz .LBB0_776
	s_and_b64 vcc, exec, s[40:41]
	s_cbranch_vccnz .LBB0_770
	v_mul_f32_e32 v8, v224, v235
	v_sin_f32_e32 v13, v8
	v_mul_f32_e32 v9, v224, v228
	v_sin_f32_e32 v80, v9
	v_cos_f32_e32 v12, v9
	v_mul_f32_e32 v9, v223, v235
	v_readlane_b32 s36, v254, 50
	ds_bpermute_b32 v10, v219, v82
	v_sin_f32_e32 v15, v9
	ds_bpermute_b32 v11, v219, v83
	v_readlane_b32 s37, v254, 51
	ds_bpermute_b32 v14, v219, v160
	ds_bpermute_b32 v171, v219, v85
	v_cndmask_b32_e64 v164, -v13, v13, s[36:37]
	v_mul_f32_e32 v13, v223, v228
	v_sin_f32_e32 v87, v13
	v_cndmask_b32_e64 v165, -v15, v15, s[36:37]
	ds_bpermute_b32 v15, v219, v161
	s_waitcnt lgkmcnt(0)
	v_pk_mul_f32 v[10:11], v[164:165], v[10:11]
	v_cndmask_b32_e64 v164, -v80, v80, s[36:37]
	v_mul_f32_e32 v80, v203, v235
	v_cndmask_b32_e64 v165, -v87, v87, s[36:37]
	v_cos_f32_e32 v87, v80
	v_sin_f32_e32 v80, v80
	v_pk_mul_f32 v[14:15], v[164:165], v[14:15]
	ds_bpermute_b32 v165, v219, v84
	v_mul_f32_e32 v164, v87, v84
	v_mul_f32_e32 v87, v203, v228
	v_cos_f32_e32 v167, v87
	v_cndmask_b32_e64 v80, -v80, v80, s[36:37]
	s_waitcnt lgkmcnt(0)
	v_mul_f32_e32 v166, v80, v165
	v_mul_f32_e32 v165, v175, v235
	v_mul_f32_e32 v168, v167, v162
	v_sin_f32_e32 v167, v165
	v_cos_f32_e32 v8, v8
	v_cos_f32_e32 v9, v9
	v_sin_f32_e32 v87, v87
	ds_bpermute_b32 v80, v219, v162
	v_cos_f32_e32 v178, v165
	v_cndmask_b32_e64 v179, -v167, v167, s[36:37]
	v_mov_b32_e32 v170, v85
	v_cndmask_b32_e64 v87, -v87, v87, s[36:37]
	v_pk_mul_f32 v[170:171], v[178:179], v[170:171]
	v_pk_fma_f32 v[8:9], v[8:9], v[82:83], v[10:11]
	v_mul_f32_e32 v10, v175, v228
	s_waitcnt lgkmcnt(0)
	v_mul_f32_e32 v182, v87, v80
	v_mov_b32_e32 v167, v171
	v_sin_f32_e32 v80, v10
	ds_bpermute_b32 v171, v219, v163
	v_cos_f32_e32 v178, v10
	v_cos_f32_e32 v13, v13
	v_mov_b32_e32 v165, v170
	v_cndmask_b32_e64 v179, -v80, v80, s[36:37]
	v_mov_b32_e32 v170, v163
	v_pk_add_f32 v[10:11], v[164:165], v[166:167]
	s_waitcnt lgkmcnt(0)
	v_pk_mul_f32 v[164:165], v[178:179], v[170:171]
	v_pk_fma_f32 v[12:13], v[12:13], v[160:161], v[14:15]
	v_mov_b32_e32 v169, v164
	v_mov_b32_e32 v183, v165
	v_pk_add_f32 v[14:15], v[168:169], v[182:183]
	s_branch .LBB0_771

.LBB0_840:
	ds_bpermute_b32 v80, v231, v192
	ds_read_b128 v[0:3], v201
	ds_read_b128 v[4:7], v201 offset:64
	ds_read_b128 v[152:155], v201 offset:128
	s_or_b32 s90, s56, 64
	s_and_b32 s2, s90, s59
	s_lshr_b32 s0, s2, 6
	ds_read_b128 v[156:159], v201 offset:192
	s_waitcnt lgkmcnt(0)
	v_pk_fma_f32 v[84:85], v[78:79], v[80:81], v[2:3] op_sel_hi:[1,0,1]
	v_pk_fma_f32 v[82:83], v[76:77], v[80:81], v[0:1] op_sel_hi:[1,0,1]
	v_pk_fma_f32 v[160:161], v[72:73], v[80:81], v[4:5] op_sel_hi:[1,0,1]
	v_pk_fma_f32 v[162:163], v[74:75], v[80:81], v[6:7] op_sel_hi:[1,0,1]
	v_pk_fma_f32 v[152:153], v[68:69], v[80:81], v[152:153] op_sel_hi:[1,0,1]
	v_pk_fma_f32 v[154:155], v[70:71], v[80:81], v[154:155] op_sel_hi:[1,0,1]
	s_waitcnt lgkmcnt(0)
	v_pk_fma_f32 v[156:157], v[64:65], v[80:81], v[156:157] op_sel_hi:[1,0,1]
	v_pk_fma_f32 v[158:159], v[66:67], v[80:81], v[158:159] op_sel_hi:[1,0,1]
	v_cvt_f32_ubyte0_e32 v231, s0
	s_and_b64 vcc, exec, s[48:49]
	s_mov_b64 s[44:45], -1
	s_cbranch_vccnz .LBB0_891
	s_and_b64 vcc, exec, s[46:47]
	s_cbranch_vccnz .LBB0_885
	s_andn2_b64 vcc, exec, s[26:27]
	s_cbranch_vccnz .LBB0_882
	v_readlane_b32 s36, v254, 34
	v_readlane_b32 s37, v254, 35
	s_andn2_b64 vcc, exec, s[36:37]
	s_cbranch_vccnz .LBB0_876
	s_cmp_lt_i32 s58, 10
	s_cbranch_scc1 .LBB0_870
	s_cmp_lg_u32 s58, 10
	s_cbranch_scc0 .LBB0_867
	v_readlane_b32 s36, v254, 44
	v_readlane_b32 s37, v254, 45
	s_andn2_b64 vcc, exec, s[36:37]
	s_cbranch_vccnz .LBB0_862
	s_cmp_gt_i32 s58, 21
	s_cbranch_scc0 .LBB0_854
	v_readlane_b32 s36, v255, 0
	v_readlane_b32 s37, v255, 1
	s_andn2_b64 vcc, exec, s[36:37]
	s_cbranch_vccnz .LBB0_853
	s_and_b64 vcc, exec, s[40:41]
	s_cbranch_vccnz .LBB0_851
	v_mul_f32_e32 v0, v224, v231
	v_sin_f32_e32 v5, v0
	v_mul_f32_e32 v1, v224, v229
	v_sin_f32_e32 v80, v1
	v_cos_f32_e32 v4, v1
	v_mul_f32_e32 v1, v223, v231
	v_readlane_b32 s36, v254, 50
	ds_bpermute_b32 v2, v219, v82
	v_sin_f32_e32 v7, v1
	ds_bpermute_b32 v3, v219, v83
	v_readlane_b32 s37, v254, 51
	ds_bpermute_b32 v6, v219, v160
	ds_bpermute_b32 v171, v219, v85
	v_cndmask_b32_e64 v164, -v5, v5, s[36:37]
	v_mul_f32_e32 v5, v223, v229
	v_sin_f32_e32 v87, v5
	v_cndmask_b32_e64 v165, -v7, v7, s[36:37]
	ds_bpermute_b32 v7, v219, v161
	s_waitcnt lgkmcnt(0)
	v_pk_mul_f32 v[2:3], v[164:165], v[2:3]
	v_cndmask_b32_e64 v164, -v80, v80, s[36:37]
	v_mul_f32_e32 v80, v203, v231
	v_cndmask_b32_e64 v165, -v87, v87, s[36:37]
	v_cos_f32_e32 v87, v80
	v_sin_f32_e32 v80, v80
	v_pk_mul_f32 v[6:7], v[164:165], v[6:7]
	ds_bpermute_b32 v165, v219, v84
	v_mul_f32_e32 v164, v87, v84
	v_mul_f32_e32 v87, v203, v229
	v_cos_f32_e32 v167, v87
	v_cndmask_b32_e64 v80, -v80, v80, s[36:37]
	s_waitcnt lgkmcnt(0)
	v_mul_f32_e32 v166, v80, v165
	v_mul_f32_e32 v165, v175, v231
	v_mul_f32_e32 v168, v167, v162
	v_sin_f32_e32 v167, v165
	v_cos_f32_e32 v0, v0
	v_cos_f32_e32 v1, v1
	v_sin_f32_e32 v87, v87
	ds_bpermute_b32 v80, v219, v162
	v_cos_f32_e32 v178, v165
	v_cndmask_b32_e64 v179, -v167, v167, s[36:37]
	v_mov_b32_e32 v170, v85
	v_cndmask_b32_e64 v87, -v87, v87, s[36:37]
	v_pk_mul_f32 v[170:171], v[178:179], v[170:171]
	v_pk_fma_f32 v[0:1], v[0:1], v[82:83], v[2:3]
	v_mul_f32_e32 v2, v175, v229
	s_waitcnt lgkmcnt(0)
	v_mul_f32_e32 v182, v87, v80
	v_mov_b32_e32 v167, v171
	v_sin_f32_e32 v80, v2
	ds_bpermute_b32 v171, v219, v163
	v_cos_f32_e32 v178, v2
	v_cos_f32_e32 v5, v5
	v_mov_b32_e32 v165, v170
	v_cndmask_b32_e64 v179, -v80, v80, s[36:37]
	v_mov_b32_e32 v170, v163
	v_pk_add_f32 v[2:3], v[164:165], v[166:167]
	s_waitcnt lgkmcnt(0)
	v_pk_mul_f32 v[164:165], v[178:179], v[170:171]
	v_pk_fma_f32 v[4:5], v[4:5], v[160:161], v[6:7]
	v_mov_b32_e32 v169, v164
	v_mov_b32_e32 v183, v165
	v_pk_add_f32 v[6:7], v[168:169], v[182:183]
	s_branch .LBB0_852

.LBB0_895:
	ds_bpermute_b32 v80, v232, v192
	ds_read_b128 v[8:11], v201
	ds_read_b128 v[12:15], v201 offset:64
	ds_read_b128 v[152:155], v201 offset:128
	s_and_b64 vcc, exec, s[48:49]
	s_mov_b64 s[44:45], -1
	ds_read_b128 v[156:159], v201 offset:192
	s_waitcnt lgkmcnt(0)
	v_pk_fma_f32 v[84:85], v[62:63], v[80:81], v[10:11] op_sel_hi:[1,0,1]
	v_pk_fma_f32 v[82:83], v[60:61], v[80:81], v[8:9] op_sel_hi:[1,0,1]
	v_pk_fma_f32 v[160:161], v[56:57], v[80:81], v[12:13] op_sel_hi:[1,0,1]
	v_pk_fma_f32 v[162:163], v[58:59], v[80:81], v[14:15] op_sel_hi:[1,0,1]
	v_pk_fma_f32 v[152:153], v[52:53], v[80:81], v[152:153] op_sel_hi:[1,0,1]
	v_pk_fma_f32 v[154:155], v[54:55], v[80:81], v[154:155] op_sel_hi:[1,0,1]
	s_waitcnt lgkmcnt(0)
	v_pk_fma_f32 v[156:157], v[48:49], v[80:81], v[156:157] op_sel_hi:[1,0,1]
	v_pk_fma_f32 v[158:159], v[50:51], v[80:81], v[158:159] op_sel_hi:[1,0,1]
	s_cbranch_vccnz .LBB0_970
	s_and_b64 vcc, exec, s[46:47]
	s_cbranch_vccnz .LBB0_963
	s_andn2_b64 vcc, exec, s[26:27]
	s_cbranch_vccnz .LBB0_959
	v_readlane_b32 s36, v254, 34
	v_readlane_b32 s37, v254, 35
	s_andn2_b64 vcc, exec, s[36:37]
	s_cbranch_vccnz .LBB0_952
	s_cmp_lt_i32 s58, 10
	s_cbranch_scc1 .LBB0_939
	s_cmp_lg_u32 s58, 10
	s_cbranch_scc0 .LBB0_929
	v_readlane_b32 s36, v254, 44
	v_readlane_b32 s37, v254, 45
	s_andn2_b64 vcc, exec, s[36:37]
	s_cbranch_vccnz .LBB0_923
	s_cmp_gt_i32 s58, 21
	s_cbranch_scc0 .LBB0_913
	v_readlane_b32 s36, v255, 0
	v_readlane_b32 s37, v255, 1
	s_andn2_b64 vcc, exec, s[36:37]
	s_cbranch_vccnz .LBB0_912
	s_and_b64 vcc, exec, s[40:41]
	s_cbranch_vccnz .LBB0_906
	v_mul_f32_e32 v8, v224, v231
	v_sin_f32_e32 v13, v8
	v_mul_f32_e32 v9, v224, v227
	v_sin_f32_e32 v80, v9
	v_cos_f32_e32 v12, v9
	v_mul_f32_e32 v9, v223, v231
	v_readlane_b32 s36, v254, 50
	ds_bpermute_b32 v10, v219, v82
	v_sin_f32_e32 v15, v9
	ds_bpermute_b32 v11, v219, v83
	v_readlane_b32 s37, v254, 51
	ds_bpermute_b32 v14, v219, v160
	ds_bpermute_b32 v171, v219, v85
	v_cndmask_b32_e64 v164, -v13, v13, s[36:37]
	v_mul_f32_e32 v13, v223, v227
	v_sin_f32_e32 v87, v13
	v_cndmask_b32_e64 v165, -v15, v15, s[36:37]
	ds_bpermute_b32 v15, v219, v161
	s_waitcnt lgkmcnt(0)
	v_pk_mul_f32 v[10:11], v[164:165], v[10:11]
	v_cndmask_b32_e64 v164, -v80, v80, s[36:37]
	v_mul_f32_e32 v80, v203, v231
	v_cndmask_b32_e64 v165, -v87, v87, s[36:37]
	v_cos_f32_e32 v87, v80
	v_sin_f32_e32 v80, v80
	v_pk_mul_f32 v[14:15], v[164:165], v[14:15]
	ds_bpermute_b32 v165, v219, v84
	v_mul_f32_e32 v164, v87, v84
	v_mul_f32_e32 v87, v203, v227
	v_cos_f32_e32 v167, v87
	v_cndmask_b32_e64 v80, -v80, v80, s[36:37]
	s_waitcnt lgkmcnt(0)
	v_mul_f32_e32 v166, v80, v165
	v_mul_f32_e32 v165, v175, v231
	v_mul_f32_e32 v168, v167, v162
	v_sin_f32_e32 v167, v165
	v_cos_f32_e32 v8, v8
	v_cos_f32_e32 v9, v9
	v_sin_f32_e32 v87, v87
	ds_bpermute_b32 v80, v219, v162
	v_cos_f32_e32 v178, v165
	v_cndmask_b32_e64 v179, -v167, v167, s[36:37]
	v_mov_b32_e32 v170, v85
	v_cndmask_b32_e64 v87, -v87, v87, s[36:37]
	v_pk_mul_f32 v[170:171], v[178:179], v[170:171]
	v_pk_fma_f32 v[8:9], v[8:9], v[82:83], v[10:11]
	v_mul_f32_e32 v10, v175, v227
	s_waitcnt lgkmcnt(0)
	v_mul_f32_e32 v182, v87, v80
	v_mov_b32_e32 v167, v171
	v_sin_f32_e32 v80, v10
	ds_bpermute_b32 v171, v219, v163
	v_cos_f32_e32 v178, v10
	v_cos_f32_e32 v13, v13
	v_mov_b32_e32 v165, v170
	v_cndmask_b32_e64 v179, -v80, v80, s[36:37]
	v_mov_b32_e32 v170, v163
	v_pk_add_f32 v[10:11], v[164:165], v[166:167]
	s_waitcnt lgkmcnt(0)
	v_pk_mul_f32 v[164:165], v[178:179], v[170:171]
	v_pk_fma_f32 v[12:13], v[12:13], v[160:161], v[14:15]
	v_mov_b32_e32 v169, v164
	v_mov_b32_e32 v183, v165
	v_pk_add_f32 v[14:15], v[168:169], v[182:183]
	s_branch .LBB0_907

.LBB0_976:
	ds_bpermute_b32 v80, v233, v192
	ds_read_b128 v[0:3], v201
	ds_read_b128 v[4:7], v201 offset:64
	ds_read_b128 v[152:155], v201 offset:128
	s_or_b32 s56, s56, 0x60
	s_and_b32 s2, s56, s59
	s_lshr_b32 s0, s2, 6
	ds_read_b128 v[156:159], v201 offset:192
	s_waitcnt lgkmcnt(0)
	v_pk_fma_f32 v[84:85], v[46:47], v[80:81], v[2:3] op_sel_hi:[1,0,1]
	v_pk_fma_f32 v[82:83], v[44:45], v[80:81], v[0:1] op_sel_hi:[1,0,1]
	v_pk_fma_f32 v[160:161], v[40:41], v[80:81], v[4:5] op_sel_hi:[1,0,1]
	v_pk_fma_f32 v[162:163], v[42:43], v[80:81], v[6:7] op_sel_hi:[1,0,1]
	v_pk_fma_f32 v[152:153], v[36:37], v[80:81], v[152:153] op_sel_hi:[1,0,1]
	v_pk_fma_f32 v[154:155], v[38:39], v[80:81], v[154:155] op_sel_hi:[1,0,1]
	s_waitcnt lgkmcnt(0)
	v_pk_fma_f32 v[156:157], v[32:33], v[80:81], v[156:157] op_sel_hi:[1,0,1]
	v_pk_fma_f32 v[158:159], v[34:35], v[80:81], v[158:159] op_sel_hi:[1,0,1]
	v_cvt_f32_ubyte0_e32 v227, s0
	s_and_b64 vcc, exec, s[48:49]
	s_mov_b64 s[44:45], -1
	s_cbranch_vccnz .LBB0_1027
	s_and_b64 vcc, exec, s[46:47]
	s_cbranch_vccnz .LBB0_1021
	s_andn2_b64 vcc, exec, s[26:27]
	s_cbranch_vccnz .LBB0_1018
	v_readlane_b32 s36, v254, 34
	v_readlane_b32 s37, v254, 35
	s_andn2_b64 vcc, exec, s[36:37]
	s_cbranch_vccnz .LBB0_1012
	s_cmp_lt_i32 s58, 10
	s_cbranch_scc1 .LBB0_1006
	s_cmp_lg_u32 s58, 10
	s_cbranch_scc0 .LBB0_1003
	v_readlane_b32 s36, v254, 44
	v_readlane_b32 s37, v254, 45
	s_andn2_b64 vcc, exec, s[36:37]
	s_cbranch_vccnz .LBB0_998
	s_cmp_gt_i32 s58, 21
	s_cbranch_scc0 .LBB0_990
	v_readlane_b32 s36, v255, 0
	v_readlane_b32 s37, v255, 1
	s_andn2_b64 vcc, exec, s[36:37]
	s_cbranch_vccnz .LBB0_989
	s_and_b64 vcc, exec, s[40:41]
	s_cbranch_vccnz .LBB0_987
	v_mul_f32_e32 v0, v224, v227
	v_sin_f32_e32 v5, v0
	v_mul_f32_e32 v1, v224, v230
	v_sin_f32_e32 v80, v1
	v_cos_f32_e32 v4, v1
	v_mul_f32_e32 v1, v223, v227
	v_readlane_b32 s36, v254, 50
	ds_bpermute_b32 v2, v219, v82
	v_sin_f32_e32 v7, v1
	ds_bpermute_b32 v3, v219, v83
	v_readlane_b32 s37, v254, 51
	ds_bpermute_b32 v6, v219, v160
	ds_bpermute_b32 v171, v219, v85
	v_cndmask_b32_e64 v164, -v5, v5, s[36:37]
	v_mul_f32_e32 v5, v223, v230
	v_sin_f32_e32 v87, v5
	v_cndmask_b32_e64 v165, -v7, v7, s[36:37]
	ds_bpermute_b32 v7, v219, v161
	s_waitcnt lgkmcnt(0)
	v_pk_mul_f32 v[2:3], v[164:165], v[2:3]
	v_cndmask_b32_e64 v164, -v80, v80, s[36:37]
	v_mul_f32_e32 v80, v203, v227
	v_cndmask_b32_e64 v165, -v87, v87, s[36:37]
	v_cos_f32_e32 v87, v80
	v_sin_f32_e32 v80, v80
	v_pk_mul_f32 v[6:7], v[164:165], v[6:7]
	ds_bpermute_b32 v165, v219, v84
	v_mul_f32_e32 v164, v87, v84
	v_mul_f32_e32 v87, v203, v230
	v_cos_f32_e32 v167, v87
	v_cndmask_b32_e64 v80, -v80, v80, s[36:37]
	s_waitcnt lgkmcnt(0)
	v_mul_f32_e32 v166, v80, v165
	v_mul_f32_e32 v165, v175, v227
	v_mul_f32_e32 v168, v167, v162
	v_sin_f32_e32 v167, v165
	v_cos_f32_e32 v0, v0
	v_cos_f32_e32 v1, v1
	v_sin_f32_e32 v87, v87
	ds_bpermute_b32 v80, v219, v162
	v_cos_f32_e32 v178, v165
	v_cndmask_b32_e64 v179, -v167, v167, s[36:37]
	v_mov_b32_e32 v170, v85
	v_cndmask_b32_e64 v87, -v87, v87, s[36:37]
	v_pk_mul_f32 v[170:171], v[178:179], v[170:171]
	v_pk_fma_f32 v[0:1], v[0:1], v[82:83], v[2:3]
	v_mul_f32_e32 v2, v175, v230
	s_waitcnt lgkmcnt(0)
	v_mul_f32_e32 v182, v87, v80
	v_mov_b32_e32 v167, v171
	v_sin_f32_e32 v80, v2
	ds_bpermute_b32 v171, v219, v163
	v_cos_f32_e32 v178, v2
	v_cos_f32_e32 v5, v5
	v_mov_b32_e32 v165, v170
	v_cndmask_b32_e64 v179, -v80, v80, s[36:37]
	v_mov_b32_e32 v170, v163
	v_pk_add_f32 v[2:3], v[164:165], v[166:167]
	s_waitcnt lgkmcnt(0)
	v_pk_mul_f32 v[164:165], v[178:179], v[170:171]
	v_pk_fma_f32 v[4:5], v[4:5], v[160:161], v[6:7]
	v_mov_b32_e32 v169, v164
	v_mov_b32_e32 v183, v165
	v_pk_add_f32 v[6:7], v[168:169], v[182:183]
	s_branch .LBB0_988

.LBB0_1031:
	ds_bpermute_b32 v80, v234, v192
	ds_read_b128 v[8:11], v201
	ds_read_b128 v[12:15], v201 offset:64
	ds_read_b128 v[152:155], v201 offset:128
	s_and_b64 vcc, exec, s[48:49]
	s_mov_b64 s[44:45], -1
	ds_read_b128 v[156:159], v201 offset:192
	s_waitcnt lgkmcnt(0)
	v_pk_fma_f32 v[84:85], v[30:31], v[80:81], v[10:11] op_sel_hi:[1,0,1]
	v_pk_fma_f32 v[82:83], v[28:29], v[80:81], v[8:9] op_sel_hi:[1,0,1]
	v_pk_fma_f32 v[160:161], v[24:25], v[80:81], v[12:13] op_sel_hi:[1,0,1]
	v_pk_fma_f32 v[162:163], v[26:27], v[80:81], v[14:15] op_sel_hi:[1,0,1]
	v_pk_fma_f32 v[152:153], v[16:17], v[80:81], v[152:153] op_sel_hi:[1,0,1]
	v_pk_fma_f32 v[154:155], v[18:19], v[80:81], v[154:155] op_sel_hi:[1,0,1]
	s_waitcnt lgkmcnt(0)
	v_pk_fma_f32 v[156:157], v[20:21], v[80:81], v[156:157] op_sel_hi:[1,0,1]
	v_pk_fma_f32 v[158:159], v[22:23], v[80:81], v[158:159] op_sel_hi:[1,0,1]
	s_cbranch_vccnz .LBB0_1106
	s_and_b64 vcc, exec, s[46:47]
	s_cbranch_vccnz .LBB0_1099
	s_andn2_b64 vcc, exec, s[26:27]
	s_cbranch_vccnz .LBB0_1095
	v_readlane_b32 s26, v254, 34
	v_readlane_b32 s27, v254, 35
	s_andn2_b64 vcc, exec, s[26:27]
	s_cbranch_vccnz .LBB0_1088
	s_cmp_lt_i32 s58, 10
	s_cbranch_scc1 .LBB0_1075
	s_cmp_lg_u32 s58, 10
	s_cbranch_scc0 .LBB0_1065
	v_readlane_b32 s26, v254, 44
	v_readlane_b32 s27, v254, 45
	s_andn2_b64 vcc, exec, s[26:27]
	s_cbranch_vccnz .LBB0_1059
	s_cmp_gt_i32 s58, 21
	s_cbranch_scc0 .LBB0_1049
	v_readlane_b32 s26, v255, 0
	v_readlane_b32 s27, v255, 1
	s_andn2_b64 vcc, exec, s[26:27]
	s_cbranch_vccnz .LBB0_1048
	s_and_b64 vcc, exec, s[40:41]
	s_cbranch_vccnz .LBB0_1042
	v_mul_f32_e32 v8, v224, v227
	v_sin_f32_e32 v13, v8
	v_mul_f32_e32 v9, v224, v228
	v_sin_f32_e32 v80, v9
	v_cos_f32_e32 v12, v9
	v_mul_f32_e32 v9, v223, v227
	v_readlane_b32 s26, v254, 50
	ds_bpermute_b32 v10, v219, v82
	v_sin_f32_e32 v15, v9
	ds_bpermute_b32 v11, v219, v83
	v_readlane_b32 s27, v254, 51
	ds_bpermute_b32 v14, v219, v160
	ds_bpermute_b32 v171, v219, v85
	v_cndmask_b32_e64 v164, -v13, v13, s[26:27]
	v_mul_f32_e32 v13, v223, v228
	v_sin_f32_e32 v87, v13
	v_cndmask_b32_e64 v165, -v15, v15, s[26:27]
	ds_bpermute_b32 v15, v219, v161
	s_waitcnt lgkmcnt(0)
	v_pk_mul_f32 v[10:11], v[164:165], v[10:11]
	v_cndmask_b32_e64 v164, -v80, v80, s[26:27]
	v_mul_f32_e32 v80, v203, v227
	v_cndmask_b32_e64 v165, -v87, v87, s[26:27]
	v_cos_f32_e32 v87, v80
	v_sin_f32_e32 v80, v80
	v_pk_mul_f32 v[14:15], v[164:165], v[14:15]
	ds_bpermute_b32 v165, v219, v84
	v_mul_f32_e32 v164, v87, v84
	v_mul_f32_e32 v87, v203, v228
	v_cos_f32_e32 v167, v87
	v_cndmask_b32_e64 v80, -v80, v80, s[26:27]
	s_waitcnt lgkmcnt(0)
	v_mul_f32_e32 v166, v80, v165
	v_mul_f32_e32 v165, v175, v227
	v_mul_f32_e32 v168, v167, v162
	v_sin_f32_e32 v167, v165
	v_cos_f32_e32 v8, v8
	v_cos_f32_e32 v9, v9
	v_sin_f32_e32 v87, v87
	ds_bpermute_b32 v80, v219, v162
	v_cos_f32_e32 v178, v165
	v_cndmask_b32_e64 v179, -v167, v167, s[26:27]
	v_mov_b32_e32 v170, v85
	v_cndmask_b32_e64 v87, -v87, v87, s[26:27]
	v_pk_mul_f32 v[170:171], v[178:179], v[170:171]
	v_pk_fma_f32 v[8:9], v[8:9], v[82:83], v[10:11]
	v_mul_f32_e32 v10, v175, v228
	s_waitcnt lgkmcnt(0)
	v_mul_f32_e32 v182, v87, v80
	v_mov_b32_e32 v167, v171
	v_sin_f32_e32 v80, v10
	ds_bpermute_b32 v171, v219, v163
	v_cos_f32_e32 v178, v10
	v_cos_f32_e32 v13, v13
	v_mov_b32_e32 v165, v170
	v_cndmask_b32_e64 v179, -v80, v80, s[26:27]
	v_mov_b32_e32 v170, v163
	v_pk_add_f32 v[10:11], v[164:165], v[166:167]
	s_waitcnt lgkmcnt(0)
	v_pk_mul_f32 v[164:165], v[178:179], v[170:171]
	v_pk_fma_f32 v[12:13], v[12:13], v[160:161], v[14:15]
	v_mov_b32_e32 v169, v164
	v_mov_b32_e32 v183, v165
	v_pk_add_f32 v[14:15], v[168:169], v[182:183]
	s_branch .LBB0_1043
